# v18 + up-GEMM epilogues (both layers): conv-weight loads of the ai=1 half issued before the four write-through ACT stores of ai=0, first-use wait vmcnt(4) instead of vmcnt(0) (no store drain mid-epilo
# speedup vs baseline: 1.0044x; 1.0044x over previous
; #define PG8_LAS __attribute__((address_space(3)))
; __device__ __forceinline__ void st16_wt(void* p, f32x4 v) { asm volatile("global_store_dwordx4 %0, %1, off sc1\n\ts_nop 1" :: "v"(p), "v"(v) : "memory"); }
;     __device__ __forceinline__ void operator()(const f32x4 (&acc)[2][2][4][2], const Unit& u, int wr, int wc, int fr, int fq) const {
;     ...
;                 const f32x4 w0 = *(const f32x4*)(cw + c), w1 = *(const f32x4*)(cw + DFFC + c), w2 = *(const f32x4*)(cw + 2 * DFFC + c), bb = *(const f32x4*)(cb + c);
;                 f32x4 h2, h3;
;                 if (!prompt) { h2 = *(const f32x4*)(state + ((size_t)sb * 2 + 0) * DFFC + c); h3 = *(const f32x4*)(state + ((size_t)sb * 2 + 1) * DFFC + c); }
;                 else if (blk > 0) { h2 = *(const PG8_LAS f32x4*)(xch + (((blk - 1) * 2 + 0) * 4 + wc) * 32 + 8 * fq + 4 * n); h3 = *(const PG8_LAS f32x4*)(xch + (((blk - 1) * 2 + 1) * 4 + wc) * 32 + 8 * fq + 4 * n); }
;                 else { h2 = (f32x4){0.f, 0.f, 0.f, 0.f}; h3 = h2; }
;                 const f32x4 a0 = acc[ai][0][0][n] * rs[ai][0], a1 = acc[ai][0][1][n] * rs[ai][1], a2 = acc[ai][0][2][n] * rs[ai][2], a3 = acc[ai][0][3][n] * rs[ai][3];
;     ...
;             for (int m = 0; m < 4; ++m) { if (!(pend && fr == 0 && m < 2)) { u32x4 w; w.x = pk[m][0].x; w.y = pk[m][0].y; w.z = pk[m][1].x; w.w = pk[m][1].y; st16_wt(ACT + (row0 + m) * DFFC + col, __builtin_bit_cast(f32x4, w)); } }
.LBB0_432:
	s_or_b64 exec, exec, s[0:1]
	global_load_dwordx4 v[222:225], v[204:205], off
	global_load_dwordx4 v[226:229], v[210:211], off
	global_load_dwordx4 v[214:217], v[212:213], off
	global_load_dwordx4 v[162:165], v[206:207], off
	s_ashr_i32 s53, s52, 31
	s_lshl_b64 s[6:7], s[52:53], 8
	s_xor_b64 s[0:1], s[30:31], -1
	v_lshl_add_u64 v[132:133], s[6:7], 0, v[192:193]
	s_and_saveexec_b64 s[6:7], s[0:1]
	s_xor_b64 s[0:1], exec, s[6:7]
	s_cbranch_execz .LBB0_434
	v_mad_u64_u32 v[130:131], s[6:7], v132, s76, 0
	v_readlane_b32 s6, v249, 7
	v_readlane_b32 s7, v249, 8
	v_mad_i32_i24 v131, v133, s76, v131
	s_nop 0
	v_mov_b64_e32 v[134:135], s[6:7]
	v_mad_u64_u32 v[134:135], s[6:7], v132, s76, v[134:135]
	v_mad_i32_i24 v135, v133, s76, v135
	v_lshl_add_u64 v[132:133], v[198:199], 1, v[134:135]
	global_store_dwordx4 v[132:133], v[150:153], off sc1
	s_nop 1
	s_mov_b64 s[6:7], 0x2c00
	v_lshl_add_u64 v[132:133], v[132:133], 0, s[6:7]
	global_store_dwordx4 v[132:133], v[146:149], off sc1
	s_nop 1
.LBB0_434:
	s_andn2_saveexec_b64 s[0:1], s[0:1]
	v_mad_u64_u32 v[130:131], s[6:7], v132, s76, 0
	v_mad_i32_i24 v131, v133, s76, v131
	s_or_b64 exec, exec, s[0:1]
	v_readlane_b32 s0, v249, 7
	v_readlane_b32 s1, v249, 8
	s_add_i32 s55, s55, s80
	s_mul_hi_i32 s53, s55, 0xb000
	v_lshl_add_u64 v[130:131], s[0:1], 0, v[130:131]
	v_lshl_add_u64 v[176:177], v[198:199], 1, v[130:131]
	s_mov_b64 s[0:1], 0x5800
	v_lshl_add_u64 v[130:131], v[176:177], 0, s[0:1]
	global_store_dwordx4 v[130:131], v[142:145], off sc1
	s_nop 1
	s_mov_b64 s[0:1], 0x8400
	v_lshl_add_u64 v[130:131], v[176:177], 0, s[0:1]
	global_store_dwordx4 v[130:131], v[138:141], off sc1
	s_nop 1
	s_mul_i32 s55, s55, 0xb000
	s_and_b64 vcc, exec, s[14:15]
	s_mov_b64 s[0:1], -1
	s_cbranch_vccnz .LBB0_438
	v_readlane_b32 s36, v250, 41
	v_readlane_b32 s48, v250, 53
	v_readlane_b32 s49, v250, 54
	s_mov_b64 s[64:65], s[48:49]
	s_add_u32 s0, s64, s55
	s_addc_u32 s1, s65, s53
	v_lshl_add_u64 v[142:143], v[198:199], 2, s[0:1]
	v_add_co_u32_e32 v144, vcc, 0x5000, v142
	s_mov_b64 s[0:1], 0
	s_nop 0
	v_addc_co_u32_e32 v145, vcc, 0, v143, vcc
	global_load_dwordx4 v[158:161], v[142:143], off
	global_load_dwordx4 v[154:157], v[144:145], off offset:2048
	v_readlane_b32 s37, v250, 42
	v_readlane_b32 s38, v250, 43
	v_readlane_b32 s39, v250, 44
	v_readlane_b32 s40, v250, 45
	v_readlane_b32 s41, v250, 46
	v_readlane_b32 s42, v250, 47
	v_readlane_b32 s43, v250, 48
	v_readlane_b32 s44, v250, 49
	v_readlane_b32 s45, v250, 50
	v_readlane_b32 s46, v250, 51
	v_readlane_b32 s47, v250, 52
	v_readlane_b32 s50, v250, 55
	v_readlane_b32 s51, v250, 56
	s_waitcnt vmcnt(0)
.LBB0_438:
	s_andn2_b64 vcc, exec, s[0:1]
	s_cbranch_vccnz .LBB0_440
	ds_read_b128 v[158:161], v239
	ds_read_b128 v[154:157], v238
.LBB0_440:
	v_fmamk_f32 v128, v128, 0x3a000000, v244
	v_rsq_f32_e32 v180, v128
	v_fmamk_f32 v128, v129, 0x3a000000, v244
	v_rsq_f32_e32 v178, v128
	v_pk_mul_f32 v[146:147], v[44:45], v[202:203] op_sel_hi:[1,0]
	v_pk_mul_f32 v[142:143], v[36:37], v[200:201] op_sel_hi:[1,0]
	v_pk_mul_f32 v[166:167], v[60:61], v[180:181] op_sel_hi:[1,0]
	s_waitcnt vmcnt(4) lgkmcnt(1)
	v_mov_b32_e32 v150, v222
	v_mov_b32_e32 v151, v223
	v_mov_b32_e32 v152, v224
	v_mov_b32_e32 v153, v225
	v_mov_b32_e32 v138, v226
	v_mov_b32_e32 v139, v227
	v_mov_b32_e32 v140, v228
	v_mov_b32_e32 v141, v229
	v_mov_b32_e32 v134, v214
	v_mov_b32_e32 v135, v215
	v_mov_b32_e32 v136, v216
	v_mov_b32_e32 v137, v217
	v_mov_b32_e32 v130, v162
	v_mov_b32_e32 v131, v163
	v_mov_b32_e32 v132, v164
	v_mov_b32_e32 v133, v165
	v_mov_b32_dpp v158, v146 row_shr:1 row_mask:0xf bank_mask:0xf
	s_waitcnt lgkmcnt(0)
	v_mov_b32_dpp v154, v142 row_shr:1 row_mask:0xf bank_mask:0xf
	v_fma_f32 v158, v150, v158, v130
	v_pk_mul_f32 v[164:165], v[52:53], v[178:179] op_sel_hi:[1,0]
	v_fmac_f32_e32 v158, v138, v154
	v_fma_f32 v154, v150, v154, v130
	v_fmac_f32_e32 v158, v166, v134
	v_fmac_f32_e32 v154, v166, v138
	v_fma_f32 v166, v166, v150, v130
	v_fma_f32 v130, v164, v150, v130
	v_fmac_f32_e32 v130, v146, v138
	v_fmac_f32_e32 v166, v164, v138
	v_fmac_f32_e32 v130, v142, v134
	v_fmac_f32_e32 v154, v164, v134
	v_fmac_f32_e32 v166, v146, v134
	v_mul_f32_e32 v134, 0x3d922279, v130
	v_fmaak_f32 v134, v130, v134, 0x3fcc422a
	v_mul_f32_e32 v134, v130, v134
	v_mul_f32_e32 v134, 0xbfb8aa3b, v134
	v_exp_f32_e32 v134, v134
	v_mov_b32_dpp v159, v147 row_shr:1 row_mask:0xf bank_mask:0xf
	v_mov_b32_dpp v155, v143 row_shr:1 row_mask:0xf bank_mask:0xf
	v_pk_mul_f32 v[148:149], v[46:47], v[202:203] op_sel_hi:[1,0]
	v_add_f32_e32 v134, 1.0, v134
	v_rcp_f32_e32 v134, v134
	v_pk_mul_f32 v[144:145], v[38:39], v[200:201] op_sel_hi:[1,0]
	v_mov_b32_dpp v160, v148 row_shr:1 row_mask:0xf bank_mask:0xf
	v_pk_mul_f32 v[162:163], v[62:63], v[180:181] op_sel_hi:[1,0]
	v_mul_f32_e32 v130, v130, v134
	v_mul_f32_e32 v134, v4, v200
	v_mul_f32_e32 v130, v134, v130
	v_fma_f32 v134, v151, v159, v131
	v_fmac_f32_e32 v134, v139, v155
	v_fmac_f32_e32 v134, v167, v135
	v_mul_f32_e32 v138, 0x3d922279, v134
	v_fmaak_f32 v138, v134, v138, 0x3fcc422a
	v_mul_f32_e32 v138, v134, v138
	v_mul_f32_e32 v138, 0xbfb8aa3b, v138
	v_exp_f32_e32 v138, v138
	v_mov_b32_dpp v156, v144 row_shr:1 row_mask:0xf bank_mask:0xf
	v_pk_mul_f32 v[128:129], v[54:55], v[178:179] op_sel_hi:[1,0]
	v_mov_b32_dpp v161, v149 row_shr:1 row_mask:0xf bank_mask:0xf
	v_add_f32_e32 v138, 1.0, v138
	v_rcp_f32_e32 v138, v138
	v_mov_b32_dpp v157, v145 row_shr:1 row_mask:0xf bank_mask:0xf
	v_mul_f32_e32 v168, 0x3d922279, v158
	v_fmaak_f32 v168, v158, v168, 0x3fcc422a
	v_mul_f32_e32 v134, v134, v138
	v_mul_f32_e32 v138, v29, v180
	v_mul_f32_e32 v134, v138, v134
	v_fma_f32 v138, v151, v155, v131
; __device__ __forceinline__ unsigned cvt_pk_bf16(float lo, float hi) { unsigned r; asm volatile("v_cvt_pk_bf16_f32 %0, %1, %2" : "=v"(r) : "v"(lo), "v"(hi)); return r; }
; __device__ __forceinline__ void st16_wt(void* p, f32x4 v) { asm volatile("global_store_dwordx4 %0, %1, off sc1\n\ts_nop 1" :: "v"(p), "v"(v) : "memory"); }
; __device__ __forceinline__ float gelu_tanh(float x) { const float u = x * (1.5957691216057308f + 0.0713548162726009f * x * x); return x * sigmoid_f(u); }
;     __device__ __forceinline__ static float dpp_up(float old, float src) { return __builtin_bit_cast(float, __builtin_amdgcn_update_dpp(__builtin_bit_cast(int, old), __builtin_bit_cast(int, src), 0x111, 0xf, 0xf, false)); }
;     __device__ __forceinline__ void operator()(const f32x4 (&acc)[2][2][4][2], const Unit& u, int wr, int wc, int fr, int fq) const {
;     ...
;                 const f32x4 a0 = acc[ai][0][0][n] * rs[ai][0], a1 = acc[ai][0][1][n] * rs[ai][1], a2 = acc[ai][0][2][n] * rs[ai][2], a3 = acc[ai][0][3][n] * rs[ai][3];
;                 f32x4 o0, o1, o2, o3;
; #pragma unroll
;                 for (int j = 0; j < 4; ++j) { const float p3 = dpp_up(h3[j], a3[j]), p2 = dpp_up(h2[j], a2[j]);
;                     o0[j] = gelu_tanh(bb[j] + w0[j] * p2 + w1[j] * p3 + w2[j] * a0[j]) * (acc[ai][1][0][n][j] * rs[ai][0]);
;                     o1[j] = gelu_tanh(bb[j] + w0[j] * p3 + w1[j] * a0[j] + w2[j] * a1[j]) * (acc[ai][1][1][n][j] * rs[ai][1]);
;                     o2[j] = gelu_tanh(bb[j] + w0[j] * a0[j] + w1[j] * a1[j] + w2[j] * a2[j]) * (acc[ai][1][2][n][j] * rs[ai][2]);
;                     o3[j] = gelu_tanh(bb[j] + w0[j] * a1[j] + w1[j] * a2[j] + w2[j] * a3[j]) * (acc[ai][1][3][n][j] * rs[ai][3]); }
;                 pk[0][n].x = cvt_pk_bf16(o0[0], o0[1]); pk[0][n].y = cvt_pk_bf16(o0[2], o0[3]); pk[1][n].x = cvt_pk_bf16(o1[0], o1[1]); pk[1][n].y = cvt_pk_bf16(o1[2], o1[3]);
;                 pk[2][n].x = cvt_pk_bf16(o2[0], o2[1]); pk[2][n].y = cvt_pk_bf16(o2[2], o2[3]); pk[3][n].x = cvt_pk_bf16(o3[0], o3[1]); pk[3][n].y = cvt_pk_bf16(o3[2], o3[3]);
;                 if (pend && fr == 0) {
;                     st16_wt(PEND + (((size_t)u.pm * 2 + 0) * 2 + 0) * DFFC + c, a0); st16_wt(PEND + (((size_t)u.pm * 2 + 0) * 2 + 1) * DFFC + c, acc[ai][1][0][n] * rs[ai][0]);
	v_fmac_f32_e32 v138, v167, v139
	v_fmac_f32_e32 v138, v165, v135
	v_mul_f32_e32 v150, 0x3d922279, v138
	v_fmaak_f32 v150, v138, v150, 0x3fcc422a
	v_mul_f32_e32 v150, v138, v150
	v_mul_f32_e32 v150, 0xbfb8aa3b, v150
	v_exp_f32_e32 v150, v150
	v_mul_f32_e32 v168, v158, v168
	v_mul_f32_e32 v168, 0xbfb8aa3b, v168
	v_exp_f32_e32 v168, v168
	v_add_f32_e32 v150, 1.0, v150
	v_rcp_f32_e32 v150, v150
	v_readlane_b32 s0, v249, 35
	v_add_f32_e32 v168, 1.0, v168
	v_rcp_f32_e32 v168, v168
	v_mul_f32_e32 v138, v138, v150
	v_mul_f32_e32 v150, v21, v178
	v_mul_f32_e32 v138, v150, v138
	v_fma_f32 v150, v167, v151, v131
	v_fma_f32 v131, v165, v151, v131
	v_fmac_f32_e32 v131, v147, v139
	v_fmac_f32_e32 v150, v165, v139
	v_fmac_f32_e32 v131, v143, v135
	v_fmac_f32_e32 v150, v147, v135
	v_mul_f32_e32 v135, 0x3d922279, v131
	v_fmaak_f32 v135, v131, v135, 0x3fcc422a
	v_mul_f32_e32 v135, v131, v135
	v_mul_f32_e32 v135, 0xbfb8aa3b, v135
	v_exp_f32_e32 v135, v135
	v_mul_f32_e32 v158, v158, v168
	v_mul_f32_e32 v168, v28, v180
	v_mul_f32_e32 v158, v168, v158
	v_add_f32_e32 v135, 1.0, v135
	v_rcp_f32_e32 v135, v135
	v_mul_f32_e32 v168, 0x3d922279, v154
	v_mul_f32_e32 v155, 0x3d922279, v150
	v_fmaak_f32 v168, v154, v168, 0x3fcc422a
	v_mul_f32_e32 v131, v131, v135
	v_mul_f32_e32 v135, v5, v200
	v_mul_f32_e32 v131, v135, v131
	v_fma_f32 v135, v152, v160, v132
	v_fmac_f32_e32 v135, v140, v156
	v_fmac_f32_e32 v135, v162, v136
	v_mul_f32_e32 v139, 0x3d922279, v135
	v_fmaak_f32 v139, v135, v139, 0x3fcc422a
	v_mul_f32_e32 v139, v135, v139
	v_mul_f32_e32 v139, 0xbfb8aa3b, v139
	v_exp_f32_e32 v139, v139
	v_fmaak_f32 v155, v150, v155, 0x3fcc422a
	v_mul_f32_e32 v168, v154, v168
	v_mul_f32_e32 v155, v150, v155
	v_add_f32_e32 v139, 1.0, v139
	v_rcp_f32_e32 v139, v139
	v_mul_f32_e32 v168, 0xbfb8aa3b, v168
	v_mul_f32_e32 v155, 0xbfb8aa3b, v155
	v_exp_f32_e32 v168, v168
	v_mul_f32_e32 v135, v135, v139
	v_mul_f32_e32 v139, v30, v180
	v_mul_f32_e32 v135, v139, v135
	v_fma_f32 v139, v152, v156, v132
	v_fmac_f32_e32 v139, v162, v140
	v_fmac_f32_e32 v139, v128, v136
	v_mul_f32_e32 v151, 0x3d922279, v139
	v_fmaak_f32 v151, v139, v151, 0x3fcc422a
	v_mul_f32_e32 v151, v139, v151
	v_mul_f32_e32 v151, 0xbfb8aa3b, v151
	v_exp_f32_e32 v151, v151
	v_exp_f32_e32 v155, v155
	v_add_f32_e32 v168, 1.0, v168
	v_rcp_f32_e32 v168, v168
	v_add_f32_e32 v151, 1.0, v151
	v_rcp_f32_e32 v151, v151
	v_add_f32_e32 v155, 1.0, v155
	v_rcp_f32_e32 v155, v155
	v_mul_f32_e32 v154, v154, v168
	v_mul_f32_e32 v139, v139, v151
	v_mul_f32_e32 v151, v22, v178
	v_mul_f32_e32 v139, v151, v139
	v_fma_f32 v151, v162, v152, v132
	v_fmac_f32_e32 v151, v128, v140
	v_fma_f32 v128, v128, v152, v132
	v_fmac_f32_e32 v128, v148, v140
	v_fmac_f32_e32 v128, v144, v136
	v_mul_f32_e32 v132, 0x3d922279, v128
	v_fmaak_f32 v132, v128, v132, 0x3fcc422a
	v_mul_f32_e32 v132, v128, v132
	v_mul_f32_e32 v132, 0xbfb8aa3b, v132
	v_exp_f32_e32 v132, v132
	v_fmac_f32_e32 v151, v148, v136
	v_mul_f32_e32 v168, v20, v178
	v_mul_f32_e32 v150, v150, v155
	v_add_f32_e32 v132, 1.0, v132
	v_rcp_f32_e32 v132, v132
	v_mul_f32_e32 v155, v13, v202
	v_mul_f32_e32 v154, v168, v154
	v_mul_f32_e32 v168, 0x3d922279, v166
	v_mul_f32_e32 v128, v128, v132
	v_mul_f32_e32 v132, v6, v200
	v_mul_f32_e32 v152, v132, v128
	v_fma_f32 v128, v153, v161, v133
	v_fmac_f32_e32 v128, v141, v157
	v_fmac_f32_e32 v128, v163, v137
	v_mul_f32_e32 v132, 0x3d922279, v128
	v_fmaak_f32 v132, v128, v132, 0x3fcc422a
	v_mul_f32_e32 v132, v128, v132
	v_mul_f32_e32 v132, 0xbfb8aa3b, v132
	v_exp_f32_e32 v132, v132
	v_mul_f32_e32 v150, v155, v150
	v_mul_f32_e32 v155, 0x3d922279, v151
	v_fmaak_f32 v168, v166, v168, 0x3fcc422a
	v_add_f32_e32 v132, 1.0, v132
	v_rcp_f32_e32 v132, v132
	v_fmaak_f32 v155, v151, v155, 0x3fcc422a
	v_mul_f32_e32 v168, v166, v168
	v_mul_f32_e32 v155, v151, v155
	v_mul_f32_e32 v128, v128, v132
	v_mul_f32_e32 v132, v31, v180
	v_mul_f32_e32 v128, v132, v128
	v_fma_f32 v132, v153, v157, v133
	v_fmac_f32_e32 v132, v163, v141
	v_fmac_f32_e32 v132, v129, v137
	v_mul_f32_e32 v136, 0x3d922279, v132
	v_fmaak_f32 v136, v132, v136, 0x3fcc422a
	v_mul_f32_e32 v136, v132, v136
	v_mul_f32_e32 v136, 0xbfb8aa3b, v136
	v_exp_f32_e32 v136, v136
	v_mul_f32_e32 v168, 0xbfb8aa3b, v168
	v_mul_f32_e32 v155, 0xbfb8aa3b, v155
	v_exp_f32_e32 v168, v168
	v_add_f32_e32 v136, 1.0, v136
	v_rcp_f32_e32 v136, v136
	v_exp_f32_e32 v155, v155
	v_add_f32_e32 v168, 1.0, v168
	v_rcp_f32_e32 v168, v168
	v_mul_f32_e32 v132, v132, v136
	v_mul_f32_e32 v136, v23, v178
	v_mul_f32_e32 v132, v136, v132
	v_fma_f32 v136, v163, v153, v133
	v_fmac_f32_e32 v133, v129, v153
	v_fmac_f32_e32 v133, v149, v141
	v_fmac_f32_e32 v136, v129, v141
	v_fmac_f32_e32 v133, v145, v137
	v_fmac_f32_e32 v136, v149, v137
	v_mul_f32_e32 v129, 0x3d922279, v133
	v_mul_f32_e32 v140, 0x3d922279, v136
	v_fmaak_f32 v129, v133, v129, 0x3fcc422a
	v_fmaak_f32 v140, v136, v140, 0x3fcc422a
	v_mul_f32_e32 v129, v133, v129
	v_mul_f32_e32 v140, v136, v140
	v_mul_f32_e32 v129, 0xbfb8aa3b, v129
	v_mul_f32_e32 v140, 0xbfb8aa3b, v140
	v_exp_f32_e32 v129, v129
	v_exp_f32_e32 v140, v140
	v_add_f32_e32 v155, 1.0, v155
	v_rcp_f32_e32 v155, v155
	v_add_f32_e32 v129, 1.0, v129
	v_add_f32_e32 v140, 1.0, v140
	v_rcp_f32_e32 v129, v129
	v_rcp_f32_e32 v140, v140
	v_readlane_b32 s1, v249, 36
	s_and_b64 s[0:1], s[0:1], s[16:17]
	v_mul_f32_e32 v129, v133, v129
	v_mul_f32_e32 v133, v7, v200
	v_mul_f32_e32 v166, v166, v168
	v_mul_f32_e32 v168, v12, v202
	v_mul_f32_e32 v151, v151, v155
	v_mul_f32_e32 v155, v14, v202
	v_mul_f32_e32 v136, v136, v140
	v_mul_f32_e32 v140, v15, v202
	v_mul_f32_e32 v129, v133, v129
	v_mul_f32_e32 v166, v168, v166
	v_mul_f32_e32 v151, v155, v151
	v_mul_f32_e32 v155, v140, v136
	v_cvt_pk_bf16_f32 v140, v158, v134
	v_cvt_pk_bf16_f32 v141, v135, v128
	v_cvt_pk_bf16_f32 v136, v154, v138
	v_cvt_pk_bf16_f32 v137, v139, v132
	v_cvt_pk_bf16_f32 v132, v166, v150
	v_cvt_pk_bf16_f32 v133, v151, v155
	v_cvt_pk_bf16_f32 v128, v130, v131
	v_cvt_pk_bf16_f32 v129, v152, v129
	s_and_saveexec_b64 s[6:7], s[8:9]
	s_cbranch_execz .LBB0_448
	s_and_b64 vcc, exec, s[14:15]
	s_cbranch_vccnz .LBB0_443
	v_readlane_b32 s16, v249, 19
	s_add_u32 s16, s16, s55
	v_readlane_b32 s17, v249, 21
	s_addc_u32 s17, s17, s53
	s_mov_b64 s[30:31], -1
	s_cbranch_execz .LBB0_444
	s_branch .LBB0_446

; #define PG8_LAS __attribute__((address_space(3)))
; __device__ __forceinline__ void st16_wt(void* p, f32x4 v) { asm volatile("global_store_dwordx4 %0, %1, off sc1\n\ts_nop 1" :: "v"(p), "v"(v) : "memory"); }
;     __device__ __forceinline__ void operator()(const f32x4 (&acc)[2][2][4][2], const Unit& u, int wr, int wc, int fr, int fq) const {
;     ...
;                 const f32x4 w0 = *(const f32x4*)(cw + c), w1 = *(const f32x4*)(cw + DFFC + c), w2 = *(const f32x4*)(cw + 2 * DFFC + c), bb = *(const f32x4*)(cb + c);
;                 f32x4 h2, h3;
;                 if (!prompt) { h2 = *(const f32x4*)(state + ((size_t)sb * 2 + 0) * DFFC + c); h3 = *(const f32x4*)(state + ((size_t)sb * 2 + 1) * DFFC + c); }
;                 else if (blk > 0) { h2 = *(const PG8_LAS f32x4*)(xch + (((blk - 1) * 2 + 0) * 4 + wc) * 32 + 8 * fq + 4 * n); h3 = *(const PG8_LAS f32x4*)(xch + (((blk - 1) * 2 + 1) * 4 + wc) * 32 + 8 * fq + 4 * n); }
;                 else { h2 = (f32x4){0.f, 0.f, 0.f, 0.f}; h3 = h2; }
;                 const f32x4 a0 = acc[ai][0][0][n] * rs[ai][0], a1 = acc[ai][0][1][n] * rs[ai][1], a2 = acc[ai][0][2][n] * rs[ai][2], a3 = acc[ai][0][3][n] * rs[ai][3];
;     ...
;             for (int m = 0; m < 4; ++m) { if (!(pend && fr == 0 && m < 2)) { u32x4 w; w.x = pk[m][0].x; w.y = pk[m][0].y; w.z = pk[m][1].x; w.w = pk[m][1].y; st16_wt(ACT + (row0 + m) * DFFC + col, __builtin_bit_cast(f32x4, w)); } }
.LBB0_1142:
	s_or_b64 exec, exec, s[14:15]
	global_load_dwordx4 v[226:229], v[206:207], off
	global_load_dwordx4 v[230:233], v[208:209], off
	global_load_dwordx4 v[214:217], v[210:211], off
	global_load_dwordx4 v[162:165], v[212:213], off
	s_ashr_i32 s17, s16, 31
	s_lshl_b64 s[14:15], s[16:17], 8
	s_xor_b64 s[8:9], s[30:31], -1
	v_lshl_add_u64 v[132:133], s[14:15], 0, v[192:193]
	s_and_saveexec_b64 s[14:15], s[8:9]
	s_xor_b64 s[14:15], exec, s[14:15]
	s_cbranch_execz .LBB0_1144
	v_mad_u64_u32 v[130:131], s[8:9], v132, s63, 0
	v_readlane_b32 s8, v249, 7
	v_readlane_b32 s9, v249, 8
	v_mad_i32_i24 v131, v133, s63, v131
	s_nop 0
	v_mov_b64_e32 v[134:135], s[8:9]
	v_mad_u64_u32 v[134:135], s[8:9], v132, s63, v[134:135]
	v_mad_i32_i24 v135, v133, s63, v135
	v_lshl_add_u64 v[132:133], v[198:199], 1, v[134:135]
	global_store_dwordx4 v[132:133], v[150:153], off sc1
	s_nop 1
	s_mov_b64 s[8:9], 0x2c00
	v_lshl_add_u64 v[132:133], v[132:133], 0, s[8:9]
	global_store_dwordx4 v[132:133], v[146:149], off sc1
	s_nop 1
.LBB0_1144:
	s_andn2_saveexec_b64 s[14:15], s[14:15]
	v_mad_u64_u32 v[130:131], s[8:9], v132, s63, 0
	v_mad_i32_i24 v131, v133, s63, v131
	s_or_b64 exec, exec, s[14:15]
	v_readlane_b32 s8, v249, 7
	v_readlane_b32 s9, v249, 8
	s_and_b64 vcc, exec, s[12:13]
	s_mov_b64 s[14:15], -1
	v_lshl_add_u64 v[130:131], s[8:9], 0, v[130:131]
	v_lshl_add_u64 v[176:177], v[198:199], 1, v[130:131]
	v_lshl_add_u64 v[130:131], v[176:177], 0, s[92:93]
	global_store_dwordx4 v[130:131], v[142:145], off sc1
	s_nop 1
	s_mov_b64 s[8:9], 0x8400
	v_lshl_add_u64 v[130:131], v[176:177], 0, s[8:9]
	global_store_dwordx4 v[130:131], v[138:141], off sc1
	s_nop 1
	s_add_i32 s9, s83, s94
	s_mul_hi_i32 s8, s9, 0xb000
	s_mul_i32 s9, s9, 0xb000
	s_cbranch_vccnz .LBB0_1148
	s_add_u32 s14, s78, s9
	s_addc_u32 s15, s79, s8
	v_lshl_add_u64 v[142:143], v[198:199], 2, s[14:15]
	v_add_co_u32_e32 v144, vcc, 0x5000, v142
	s_mov_b64 s[14:15], 0
	s_nop 0
	v_addc_co_u32_e32 v145, vcc, 0, v143, vcc
	global_load_dwordx4 v[158:161], v[142:143], off
	global_load_dwordx4 v[154:157], v[144:145], off offset:2048
	s_waitcnt vmcnt(0)
.LBB0_1148:
	s_andn2_b64 vcc, exec, s[14:15]
	s_cbranch_vccnz .LBB0_1150
	ds_read_b128 v[158:161], v243
	ds_read_b128 v[154:157], v242
.LBB0_1150:
	v_fmamk_f32 v128, v128, 0x3a000000, v248
	v_rsq_f32_e32 v180, v128
	v_fmamk_f32 v128, v129, 0x3a000000, v248
	v_rsq_f32_e32 v178, v128
	v_pk_mul_f32 v[146:147], v[44:45], v[202:203] op_sel_hi:[1,0]
	v_pk_mul_f32 v[142:143], v[36:37], v[200:201] op_sel_hi:[1,0]
	v_pk_mul_f32 v[166:167], v[60:61], v[180:181] op_sel_hi:[1,0]
	s_waitcnt vmcnt(4) lgkmcnt(1)
	v_mov_b32_e32 v150, v226
	v_mov_b32_e32 v151, v227
	v_mov_b32_e32 v152, v228
	v_mov_b32_e32 v153, v229
	v_mov_b32_e32 v138, v230
	v_mov_b32_e32 v139, v231
	v_mov_b32_e32 v140, v232
	v_mov_b32_e32 v141, v233
	v_mov_b32_e32 v134, v214
	v_mov_b32_e32 v135, v215
	v_mov_b32_e32 v136, v216
	v_mov_b32_e32 v137, v217
	v_mov_b32_e32 v130, v162
	v_mov_b32_e32 v131, v163
	v_mov_b32_e32 v132, v164
	v_mov_b32_e32 v133, v165
	v_mov_b32_dpp v158, v146 row_shr:1 row_mask:0xf bank_mask:0xf
	s_waitcnt lgkmcnt(0)
	v_mov_b32_dpp v154, v142 row_shr:1 row_mask:0xf bank_mask:0xf
	v_fma_f32 v158, v150, v158, v130
	v_pk_mul_f32 v[164:165], v[52:53], v[178:179] op_sel_hi:[1,0]
	v_fmac_f32_e32 v158, v138, v154
	v_fma_f32 v154, v150, v154, v130
	v_fmac_f32_e32 v158, v166, v134
	v_fmac_f32_e32 v154, v166, v138
	v_fma_f32 v166, v166, v150, v130
	v_fma_f32 v130, v164, v150, v130
	v_fmac_f32_e32 v130, v146, v138
	v_fmac_f32_e32 v166, v164, v138
	v_fmac_f32_e32 v130, v142, v134
	v_fmac_f32_e32 v154, v164, v134
	v_fmac_f32_e32 v166, v146, v134
	v_mul_f32_e32 v134, 0x3d922279, v130
	v_fmaak_f32 v134, v130, v134, 0x3fcc422a
	v_mul_f32_e32 v134, v130, v134
	v_mul_f32_e32 v134, 0xbfb8aa3b, v134
	v_exp_f32_e32 v134, v134
	v_mov_b32_dpp v159, v147 row_shr:1 row_mask:0xf bank_mask:0xf
	v_mov_b32_dpp v155, v143 row_shr:1 row_mask:0xf bank_mask:0xf
	v_pk_mul_f32 v[148:149], v[46:47], v[202:203] op_sel_hi:[1,0]
	v_add_f32_e32 v134, 1.0, v134
	v_rcp_f32_e32 v134, v134
	v_pk_mul_f32 v[144:145], v[38:39], v[200:201] op_sel_hi:[1,0]
	v_mov_b32_dpp v160, v148 row_shr:1 row_mask:0xf bank_mask:0xf
	v_pk_mul_f32 v[162:163], v[62:63], v[180:181] op_sel_hi:[1,0]
	v_mul_f32_e32 v130, v130, v134
	v_mul_f32_e32 v134, v4, v200
	v_mul_f32_e32 v130, v134, v130
	v_fma_f32 v134, v151, v159, v131
	v_fmac_f32_e32 v134, v139, v155
	v_fmac_f32_e32 v134, v167, v135
	v_mul_f32_e32 v138, 0x3d922279, v134
	v_fmaak_f32 v138, v134, v138, 0x3fcc422a
	v_mul_f32_e32 v138, v134, v138
	v_mul_f32_e32 v138, 0xbfb8aa3b, v138
	v_exp_f32_e32 v138, v138
	v_mov_b32_dpp v156, v144 row_shr:1 row_mask:0xf bank_mask:0xf
	v_pk_mul_f32 v[128:129], v[54:55], v[178:179] op_sel_hi:[1,0]
	v_mov_b32_dpp v161, v149 row_shr:1 row_mask:0xf bank_mask:0xf
	v_add_f32_e32 v138, 1.0, v138
	v_rcp_f32_e32 v138, v138
	v_mov_b32_dpp v157, v145 row_shr:1 row_mask:0xf bank_mask:0xf
	v_mul_f32_e32 v168, 0x3d922279, v158
	v_fmaak_f32 v168, v158, v168, 0x3fcc422a
	v_mul_f32_e32 v134, v134, v138
	v_mul_f32_e32 v138, v29, v180
	v_mul_f32_e32 v134, v138, v134
	v_fma_f32 v138, v151, v155, v131
	v_fmac_f32_e32 v138, v167, v139
	v_fmac_f32_e32 v138, v165, v135
	v_mul_f32_e32 v150, 0x3d922279, v138
	v_fmaak_f32 v150, v138, v150, 0x3fcc422a
	v_mul_f32_e32 v150, v138, v150
	v_mul_f32_e32 v150, 0xbfb8aa3b, v150
	v_exp_f32_e32 v150, v150
	v_mul_f32_e32 v168, v158, v168
	v_mul_f32_e32 v168, 0xbfb8aa3b, v168
	v_exp_f32_e32 v168, v168
	v_add_f32_e32 v150, 1.0, v150
	v_rcp_f32_e32 v150, v150
	s_and_b64 s[14:15], s[72:73], s[84:85]
	v_add_f32_e32 v168, 1.0, v168
	v_rcp_f32_e32 v168, v168
; __device__ __forceinline__ unsigned cvt_pk_bf16(float lo, float hi) { unsigned r; asm volatile("v_cvt_pk_bf16_f32 %0, %1, %2" : "=v"(r) : "v"(lo), "v"(hi)); return r; }
; __device__ __forceinline__ void st16_wt(void* p, f32x4 v) { asm volatile("global_store_dwordx4 %0, %1, off sc1\n\ts_nop 1" :: "v"(p), "v"(v) : "memory"); }
; __device__ __forceinline__ float gelu_tanh(float x) { const float u = x * (1.5957691216057308f + 0.0713548162726009f * x * x); return x * sigmoid_f(u); }
;     __device__ __forceinline__ static float dpp_up(float old, float src) { return __builtin_bit_cast(float, __builtin_amdgcn_update_dpp(__builtin_bit_cast(int, old), __builtin_bit_cast(int, src), 0x111, 0xf, 0xf, false)); }
;     __device__ __forceinline__ void operator()(const f32x4 (&acc)[2][2][4][2], const Unit& u, int wr, int wc, int fr, int fq) const {
;     ...
;                 const f32x4 a0 = acc[ai][0][0][n] * rs[ai][0], a1 = acc[ai][0][1][n] * rs[ai][1], a2 = acc[ai][0][2][n] * rs[ai][2], a3 = acc[ai][0][3][n] * rs[ai][3];
;                 f32x4 o0, o1, o2, o3;
; #pragma unroll
;                 for (int j = 0; j < 4; ++j) { const float p3 = dpp_up(h3[j], a3[j]), p2 = dpp_up(h2[j], a2[j]);
;                     o0[j] = gelu_tanh(bb[j] + w0[j] * p2 + w1[j] * p3 + w2[j] * a0[j]) * (acc[ai][1][0][n][j] * rs[ai][0]);
;                     o1[j] = gelu_tanh(bb[j] + w0[j] * p3 + w1[j] * a0[j] + w2[j] * a1[j]) * (acc[ai][1][1][n][j] * rs[ai][1]);
;                     o2[j] = gelu_tanh(bb[j] + w0[j] * a0[j] + w1[j] * a1[j] + w2[j] * a2[j]) * (acc[ai][1][2][n][j] * rs[ai][2]);
;                     o3[j] = gelu_tanh(bb[j] + w0[j] * a1[j] + w1[j] * a2[j] + w2[j] * a3[j]) * (acc[ai][1][3][n][j] * rs[ai][3]); }
;                 pk[0][n].x = cvt_pk_bf16(o0[0], o0[1]); pk[0][n].y = cvt_pk_bf16(o0[2], o0[3]); pk[1][n].x = cvt_pk_bf16(o1[0], o1[1]); pk[1][n].y = cvt_pk_bf16(o1[2], o1[3]);
;                 pk[2][n].x = cvt_pk_bf16(o2[0], o2[1]); pk[2][n].y = cvt_pk_bf16(o2[2], o2[3]); pk[3][n].x = cvt_pk_bf16(o3[0], o3[1]); pk[3][n].y = cvt_pk_bf16(o3[2], o3[3]);
;                 if (pend && fr == 0) {
;                     st16_wt(PEND + (((size_t)u.pm * 2 + 0) * 2 + 0) * DFFC + c, a0); st16_wt(PEND + (((size_t)u.pm * 2 + 0) * 2 + 1) * DFFC + c, acc[ai][1][0][n] * rs[ai][0]);
	v_mul_f32_e32 v138, v138, v150
	v_mul_f32_e32 v150, v21, v178
	v_mul_f32_e32 v138, v150, v138
	v_fma_f32 v150, v167, v151, v131
	v_fma_f32 v131, v165, v151, v131
	v_fmac_f32_e32 v131, v147, v139
	v_fmac_f32_e32 v150, v165, v139
	v_fmac_f32_e32 v131, v143, v135
	v_fmac_f32_e32 v150, v147, v135
	v_mul_f32_e32 v135, 0x3d922279, v131
	v_fmaak_f32 v135, v131, v135, 0x3fcc422a
	v_mul_f32_e32 v135, v131, v135
	v_mul_f32_e32 v135, 0xbfb8aa3b, v135
	v_exp_f32_e32 v135, v135
	v_mul_f32_e32 v158, v158, v168
	v_mul_f32_e32 v168, v28, v180
	v_mul_f32_e32 v158, v168, v158
	v_add_f32_e32 v135, 1.0, v135
	v_rcp_f32_e32 v135, v135
	v_mul_f32_e32 v168, 0x3d922279, v154
	v_mul_f32_e32 v155, 0x3d922279, v150
	v_fmaak_f32 v168, v154, v168, 0x3fcc422a
	v_mul_f32_e32 v131, v131, v135
	v_mul_f32_e32 v135, v5, v200
	v_mul_f32_e32 v131, v135, v131
	v_fma_f32 v135, v152, v160, v132
	v_fmac_f32_e32 v135, v140, v156
	v_fmac_f32_e32 v135, v162, v136
	v_mul_f32_e32 v139, 0x3d922279, v135
	v_fmaak_f32 v139, v135, v139, 0x3fcc422a
	v_mul_f32_e32 v139, v135, v139
	v_mul_f32_e32 v139, 0xbfb8aa3b, v139
	v_exp_f32_e32 v139, v139
	v_fmaak_f32 v155, v150, v155, 0x3fcc422a
	v_mul_f32_e32 v168, v154, v168
	v_mul_f32_e32 v155, v150, v155
	v_add_f32_e32 v139, 1.0, v139
	v_rcp_f32_e32 v139, v139
	v_mul_f32_e32 v168, 0xbfb8aa3b, v168
	v_mul_f32_e32 v155, 0xbfb8aa3b, v155
	v_exp_f32_e32 v168, v168
	v_mul_f32_e32 v135, v135, v139
	v_mul_f32_e32 v139, v30, v180
	v_mul_f32_e32 v135, v139, v135
	v_fma_f32 v139, v152, v156, v132
	v_fmac_f32_e32 v139, v162, v140
	v_fmac_f32_e32 v139, v128, v136
	v_mul_f32_e32 v151, 0x3d922279, v139
	v_fmaak_f32 v151, v139, v151, 0x3fcc422a
	v_mul_f32_e32 v151, v139, v151
	v_mul_f32_e32 v151, 0xbfb8aa3b, v151
	v_exp_f32_e32 v151, v151
	v_exp_f32_e32 v155, v155
	v_add_f32_e32 v168, 1.0, v168
	v_rcp_f32_e32 v168, v168
	v_add_f32_e32 v151, 1.0, v151
	v_rcp_f32_e32 v151, v151
	v_add_f32_e32 v155, 1.0, v155
	v_rcp_f32_e32 v155, v155
	v_mul_f32_e32 v154, v154, v168
	v_mul_f32_e32 v139, v139, v151
	v_mul_f32_e32 v151, v22, v178
	v_mul_f32_e32 v139, v151, v139
	v_fma_f32 v151, v162, v152, v132
	v_fmac_f32_e32 v151, v128, v140
	v_fma_f32 v128, v128, v152, v132
	v_fmac_f32_e32 v128, v148, v140
	v_fmac_f32_e32 v128, v144, v136
	v_mul_f32_e32 v132, 0x3d922279, v128
	v_fmaak_f32 v132, v128, v132, 0x3fcc422a
	v_mul_f32_e32 v132, v128, v132
	v_mul_f32_e32 v132, 0xbfb8aa3b, v132
	v_exp_f32_e32 v132, v132
	v_fmac_f32_e32 v151, v148, v136
	v_mul_f32_e32 v168, v20, v178
	v_mul_f32_e32 v150, v150, v155
	v_add_f32_e32 v132, 1.0, v132
	v_rcp_f32_e32 v132, v132
	v_mul_f32_e32 v155, v13, v202
	v_mul_f32_e32 v154, v168, v154
	v_mul_f32_e32 v168, 0x3d922279, v166
	v_mul_f32_e32 v128, v128, v132
	v_mul_f32_e32 v132, v6, v200
	v_mul_f32_e32 v152, v132, v128
	v_fma_f32 v128, v153, v161, v133
	v_fmac_f32_e32 v128, v141, v157
	v_fmac_f32_e32 v128, v163, v137
	v_mul_f32_e32 v132, 0x3d922279, v128
	v_fmaak_f32 v132, v128, v132, 0x3fcc422a
	v_mul_f32_e32 v132, v128, v132
	v_mul_f32_e32 v132, 0xbfb8aa3b, v132
	v_exp_f32_e32 v132, v132
	v_mul_f32_e32 v150, v155, v150
	v_mul_f32_e32 v155, 0x3d922279, v151
	v_fmaak_f32 v168, v166, v168, 0x3fcc422a
	v_add_f32_e32 v132, 1.0, v132
	v_rcp_f32_e32 v132, v132
	v_fmaak_f32 v155, v151, v155, 0x3fcc422a
	v_mul_f32_e32 v168, v166, v168
	v_mul_f32_e32 v155, v151, v155
	v_mul_f32_e32 v128, v128, v132
	v_mul_f32_e32 v132, v31, v180
	v_mul_f32_e32 v128, v132, v128
	v_fma_f32 v132, v153, v157, v133
	v_fmac_f32_e32 v132, v163, v141
	v_fmac_f32_e32 v132, v129, v137
	v_mul_f32_e32 v136, 0x3d922279, v132
	v_fmaak_f32 v136, v132, v136, 0x3fcc422a
	v_mul_f32_e32 v136, v132, v136
	v_mul_f32_e32 v136, 0xbfb8aa3b, v136
	v_exp_f32_e32 v136, v136
	v_mul_f32_e32 v168, 0xbfb8aa3b, v168
	v_mul_f32_e32 v155, 0xbfb8aa3b, v155
	v_exp_f32_e32 v168, v168
	v_add_f32_e32 v136, 1.0, v136
	v_rcp_f32_e32 v136, v136
	v_exp_f32_e32 v155, v155
	v_add_f32_e32 v168, 1.0, v168
	v_rcp_f32_e32 v168, v168
	v_mul_f32_e32 v132, v132, v136
	v_mul_f32_e32 v136, v23, v178
	v_mul_f32_e32 v132, v136, v132
	v_fma_f32 v136, v163, v153, v133
	v_fmac_f32_e32 v133, v129, v153
	v_fmac_f32_e32 v133, v149, v141
	v_fmac_f32_e32 v136, v129, v141
	v_fmac_f32_e32 v133, v145, v137
	v_fmac_f32_e32 v136, v149, v137
	v_mul_f32_e32 v129, 0x3d922279, v133
	v_mul_f32_e32 v140, 0x3d922279, v136
	v_fmaak_f32 v129, v133, v129, 0x3fcc422a
	v_fmaak_f32 v140, v136, v140, 0x3fcc422a
	v_mul_f32_e32 v129, v133, v129
	v_mul_f32_e32 v140, v136, v140
	v_mul_f32_e32 v129, 0xbfb8aa3b, v129
	v_mul_f32_e32 v140, 0xbfb8aa3b, v140
	v_exp_f32_e32 v129, v129
	v_exp_f32_e32 v140, v140
	v_add_f32_e32 v155, 1.0, v155
	v_rcp_f32_e32 v155, v155
	v_add_f32_e32 v129, 1.0, v129
	v_add_f32_e32 v140, 1.0, v140
	v_rcp_f32_e32 v129, v129
	v_rcp_f32_e32 v140, v140
	v_mul_f32_e32 v166, v166, v168
	v_mul_f32_e32 v168, v12, v202
	v_mul_f32_e32 v129, v133, v129
	v_mul_f32_e32 v133, v7, v200
	v_mul_f32_e32 v151, v151, v155
	v_mul_f32_e32 v155, v14, v202
	v_mul_f32_e32 v136, v136, v140
	v_mul_f32_e32 v140, v15, v202
	v_mul_f32_e32 v129, v133, v129
	v_mul_f32_e32 v166, v168, v166
	v_mul_f32_e32 v151, v155, v151
	v_mul_f32_e32 v155, v140, v136
	v_cvt_pk_bf16_f32 v140, v158, v134
	v_cvt_pk_bf16_f32 v141, v135, v128
	v_cvt_pk_bf16_f32 v136, v154, v138
	v_cvt_pk_bf16_f32 v137, v139, v132
	v_cvt_pk_bf16_f32 v132, v166, v150
	v_cvt_pk_bf16_f32 v133, v151, v155
	v_cvt_pk_bf16_f32 v128, v130, v131
	v_cvt_pk_bf16_f32 v129, v152, v129
	s_and_saveexec_b64 s[30:31], s[6:7]
	s_cbranch_execz .LBB0_1158
	s_and_b64 vcc, exec, s[12:13]
	s_cbranch_vccnz .LBB0_1153
	v_readlane_b32 s17, v249, 9
	s_add_u32 s46, s17, s9
	v_readlane_b32 s17, v249, 11
	s_addc_u32 s47, s17, s8
	s_mov_b64 s[84:85], -1
	s_cbranch_execz .LBB0_1154
	s_branch .LBB0_1156
